# phase 5: the two K=512 GEMM loops of a tile fused into one 16-stage DMA-ring loop (A address jumps from cmix to omix at stage 6; second prologue/drain removed)
# speedup vs baseline: 1.1257x; 1.0020x over previous
.LBB0_821:
	s_add_u32 s14, s14, 0x80
	s_addc_u32 s15, s15, 0
	s_add_i32 s13, s13, 1
	s_cmp_lg_u32 s13, 6
	s_cbranch_scc1 .Ldqf_0
	s_mov_b32 s32, 0xfc37fc00
	s_mov_b32 s33, -1
	v_lshl_add_u64 v[70:71], s[32:33], 0, v[70:71]
	v_lshl_add_u64 v[66:67], s[32:33], 0, v[66:67]
	v_lshl_add_u64 v[74:75], s[32:33], 0, v[74:75]
	v_lshl_add_u64 v[78:79], s[32:33], 0, v[78:79]
.Ldqf_0:
	s_add_u32 s100, s100, 0x8000
	s_cmp_lt_u32 s100, 0x14000
	s_cbranch_scc1 .Ldqr_2
	s_sub_u32 s100, s100, 0x14000

.Ldqs_2:
	s_cmp_gt_u32 s13, 14
	s_cbranch_scc1 .Ldqv_2
	s_waitcnt vmcnt(4)
	s_branch .Ldqx_2

.Ldqx_2:
	s_cmpk_lg_i32 s14, 0x800
	s_mov_b32 s31, s11
	s_waitcnt lgkmcnt(0)
	s_barrier
	s_cbranch_scc0 .LBB0_836
.LBB0_822:
	s_cmp_gt_u32 s13, 14
	s_cselect_b64 s[18:19], -1, 0
	s_and_b64 vcc, exec, s[18:19]
	s_cbranch_vccnz .LBB0_824

.Ldq_2_3:
	s_waitcnt lgkmcnt(0)
	v_mfma_f32_16x16x32_bf16 v[22:25], v[128:131], v[136:139], v[22:25]
	v_add_u32_e32 v128, s100, v119
	v_add3_u32 v148, v128, v118, s101
	v_add_u32_e32 v149, v128, v117
	v_mfma_f32_16x16x32_bf16 v[42:45], v[124:127], v[132:135], v[42:45]
	s_cmp_gt_u32 s13, 13
	s_cbranch_scc1 .Ldq_2_4
	s_add_u32 s99, s100, 0x10000
	s_cmp_lt_u32 s99, 0x14000
	s_cbranch_scc1 .Ldqw_2_4
	s_sub_u32 s99, s99, 0x14000

.Ldq_2_4:
	v_mfma_f32_16x16x32_bf16 v[34:37], v[140:143], v[132:135], v[34:37]
	v_mfma_f32_16x16x32_bf16 v[38:41], v[144:147], v[132:135], v[38:41]
	s_cmp_gt_u32 s13, 13
	s_cbranch_scc1 .Ldq_2_5
	s_add_u32 m0, s99, 0x1000
	v_lshl_add_u64 v[66:67], v[66:67], 0, v[242:243]
	global_load_lds_dwordx4 v[66:67], off
.Ldq_2_5:
	v_mfma_f32_16x16x32_bf16 v[26:29], v[124:127], v[136:139], v[26:29]
	ds_read_b128 v[124:127], v148
	v_mfma_f32_16x16x32_bf16 v[18:21], v[140:143], v[136:139], v[18:21]
	s_cmp_gt_u32 s13, 13
	s_cbranch_scc1 .Ldq_2_6
	s_add_u32 m0, s99, 0x2000
	v_lshl_add_u64 v[74:75], v[74:75], 0, v[242:243]
	global_load_lds_dwordx4 v[74:75], off
.Ldq_2_6:
	v_mfma_f32_16x16x32_bf16 v[2:5], v[144:147], v[136:139], v[2:5]
	ds_read_b128 v[128:131], v148 offset:2048
	ds_read_b128 v[132:135], v149
	ds_read_b128 v[136:139], v149 offset:2048
	ds_read_b128 v[140:143], v148 offset:4096
	ds_read_b128 v[144:147], v148 offset:6144
	s_waitcnt lgkmcnt(3)
	v_mfma_f32_16x16x32_bf16 v[46:49], v[124:127], v[132:135], v[46:49]
	s_cmp_gt_u32 s13, 13
	s_cbranch_scc1 .Ldq_2_7
	s_add_u32 m0, s99, 0x3000
	v_lshl_add_u64 v[78:79], v[78:79], 0, v[242:243]
	global_load_lds_dwordx4 v[78:79], off

.LBB0_826:
	s_andn2_b64 vcc, exec, s[20:21]
	s_cbranch_vccnz .LBB0_821
	s_add_i32 s11, s31, 0x8000
	s_and_b32 s18, s11, 0x8000
	v_or_b32_e32 v124, s18, v114
	s_branch .LBB0_821
.LBB0_836:
	v_readlane_b32 s68, v237, 3
	v_readlane_b32 s69, v237, 4
	v_add_u32_e32 v112, s10, v116
	v_or_b32_e32 v128, s12, v120
	v_readlane_b32 s70, v237, 5
	v_readlane_b32 s71, v237, 6
	s_mov_b64 s[12:13], s[68:69]
	s_waitcnt vmcnt(6)
	v_add_u32_e32 v66, 0xffffc000, v112
	v_ashrrev_i32_e32 v113, 31, v112
	v_cmp_gt_i32_e32 vcc, s29, v112
	s_mov_b64 s[14:15], s[70:71]
	v_mov_b32_e32 v130, s15
	v_cndmask_b32_e32 v67, 0, v113, vcc
	v_cndmask_b32_e32 v66, v66, v112, vcc
	v_mov_b32_e32 v131, s13
	v_mov_b32_e32 v140, s14
	v_mov_b32_e32 v142, s12
	v_ashrrev_i32_e32 v129, 31, v128
	v_cndmask_b32_e32 v69, v130, v131, vcc
	v_cndmask_b32_e32 v68, v140, v142, vcc
	v_lshlrev_b64 v[66:67], 12, v[66:67]
	v_lshl_add_u64 v[66:67], v[68:69], 0, v[66:67]
	v_lshlrev_b64 v[136:137], 2, v[128:129]
	s_waitcnt vmcnt(4)
	v_lshl_add_u64 v[78:79], v[66:67], 0, v[136:137]
	global_load_dwordx4 v[66:69], v[78:79], off
	global_load_dwordx4 v[70:73], v[78:79], off offset:16
	global_load_dwordx4 v[74:77], v[78:79], off offset:128
	s_nop 0
	global_load_dwordx4 v[78:81], v[78:79], off offset:144
	v_or_b32_e32 v152, 16, v112
	s_waitcnt vmcnt(7)
	v_add_u32_e32 v82, 0xffffc010, v112
	v_ashrrev_i32_e32 v153, 31, v152
	v_cmp_gt_i32_e32 vcc, s29, v152
	v_or_b32_e32 v154, 32, v112
	v_add_u32_e32 v108, 0xffffc020, v112
	v_cndmask_b32_e32 v83, 0, v153, vcc
	v_cndmask_b32_e32 v82, v82, v152, vcc
	v_cndmask_b32_e32 v85, v130, v131, vcc
	v_cndmask_b32_e32 v84, v140, v142, vcc
	v_or_b32_e32 v156, 48, v112
	v_ashrrev_i32_e32 v155, 31, v154
	v_cmp_gt_i32_e32 vcc, s29, v154
	v_add_u32_e32 v134, 0xffffc030, v112
	v_ashrrev_i32_e32 v157, 31, v156
	v_cndmask_b32_e32 v109, 0, v155, vcc
	v_cndmask_b32_e32 v108, v108, v154, vcc
	v_cndmask_b32_e32 v111, v130, v131, vcc
	v_cndmask_b32_e32 v110, v140, v142, vcc
	v_cmp_gt_i32_e32 vcc, s29, v156
	v_lshlrev_b64 v[82:83], 12, v[82:83]
	v_lshlrev_b64 v[108:109], 12, v[108:109]
	v_cndmask_b32_e32 v139, 0, v157, vcc
	v_cndmask_b32_e32 v138, v134, v156, vcc
	v_cndmask_b32_e32 v141, v130, v131, vcc
	v_cndmask_b32_e32 v140, v140, v142, vcc
	v_lshlrev_b64 v[138:139], 12, v[138:139]
	v_lshl_add_u64 v[82:83], v[84:85], 0, v[82:83]
	v_lshl_add_u64 v[108:109], v[110:111], 0, v[108:109]
	v_lshl_add_u64 v[138:139], v[140:141], 0, v[138:139]
	s_waitcnt vmcnt(4)
	v_lshl_add_u64 v[94:95], v[82:83], 0, v[136:137]
	v_lshl_add_u64 v[132:133], v[108:109], 0, v[136:137]
	v_lshl_add_u64 v[148:149], v[138:139], 0, v[136:137]
	global_load_dwordx4 v[82:85], v[94:95], off
	global_load_dwordx4 v[86:89], v[94:95], off offset:16
	global_load_dwordx4 v[90:93], v[94:95], off offset:144
	s_nop 0
	global_load_dwordx4 v[94:97], v[94:95], off offset:128
	s_nop 0
	global_load_dwordx4 v[108:111], v[132:133], off offset:16
	global_load_dwordx4 v[124:127], v[132:133], off
	v_lshlrev_b64 v[158:159], 1, v[128:129]
	global_load_dwordx4 v[128:131], v[132:133], off offset:144
	s_nop 0
	global_load_dwordx4 v[132:135], v[132:133], off offset:128
	s_nop 0
	global_load_dwordx4 v[136:139], v[148:149], off offset:16
	global_load_dwordx4 v[140:143], v[148:149], off
	global_load_dwordx4 v[144:147], v[148:149], off offset:144
	s_nop 0
	global_load_dwordx4 v[148:151], v[148:149], off offset:128
	v_lshlrev_b64 v[112:113], 11, v[112:113]
	v_lshl_add_u64 v[112:113], s[54:55], 0, v[112:113]
	v_lshl_add_u64 v[112:113], v[112:113], 0, v[158:159]
	v_readlane_b32 s72, v237, 7
	v_readlane_b32 s73, v237, 8
	v_readlane_b32 s74, v237, 9
	v_readlane_b32 s75, v237, 10
	v_readlane_b32 s76, v237, 11
	v_readlane_b32 s77, v237, 12
	v_readlane_b32 s78, v237, 13
	v_readlane_b32 s79, v237, 14
	v_readlane_b32 s80, v237, 15
	v_readlane_b32 s81, v237, 16
	v_readlane_b32 s82, v237, 17
	v_readlane_b32 s83, v237, 18
	s_waitcnt vmcnt(15)
	v_pk_add_f32 v[46:47], v[46:47], v[66:67]
	s_waitcnt vmcnt(14)
	v_pk_add_f32 v[58:59], v[58:59], v[70:71]
	v_pk_add_f32 v[48:49], v[48:49], v[68:69]
	v_pk_add_f32 v[60:61], v[60:61], v[72:73]
	s_waitcnt vmcnt(13)
	v_pk_add_f32 v[68:69], v[62:63], v[74:75]
	v_pk_add_f32 v[70:71], v[64:65], v[76:77]
	v_cvt_pk_bf16_f32 v62, v46, v47
	v_pk_mul_f32 v[46:47], v[46:47], v[46:47]
	v_cvt_pk_bf16_f32 v64, v58, v59
	v_pk_mul_f32 v[58:59], v[58:59], v[58:59]
	v_cvt_pk_bf16_f32 v63, v48, v49
	v_pk_mul_f32 v[48:49], v[48:49], v[48:49]
	v_cvt_pk_bf16_f32 v65, v60, v61
	v_pk_mul_f32 v[60:61], v[60:61], v[60:61]
	v_pk_mul_f32 v[72:73], v[68:69], v[68:69]
	v_add_f32_e32 v58, v58, v59
	v_add_f32_e32 v46, v46, v47
	v_cvt_pk_bf16_f32 v67, v70, v71
	v_pk_mul_f32 v[70:71], v[70:71], v[70:71]
	v_add_f32_e32 v58, v58, v60
	v_add_f32_e32 v46, v46, v48
	v_add_f32_e32 v47, v72, v73
	s_waitcnt vmcnt(12)
	v_pk_add_f32 v[54:55], v[54:55], v[78:79]
	v_add_f32_e32 v58, v58, v61
	v_add_f32_e32 v46, v46, v49
	v_add_f32_e32 v47, v47, v70
	v_cvt_pk_bf16_f32 v66, v68, v69
	v_pk_add_f32 v[56:57], v[56:57], v[80:81]
	v_cvt_pk_bf16_f32 v68, v54, v55
	v_pk_mul_f32 v[54:55], v[54:55], v[54:55]
	v_add_f32_e32 v46, v46, v58
	v_add_f32_e32 v47, v47, v71
	v_cvt_pk_bf16_f32 v69, v56, v57
	v_pk_mul_f32 v[56:57], v[56:57], v[56:57]
	v_add_f32_e32 v46, v46, v47
	v_add_f32_e32 v47, v54, v55
	v_add_f32_e32 v47, v47, v56
	v_add_f32_e32 v47, v47, v57
	v_add_f32_e32 v160, v46, v47
	s_waitcnt vmcnt(11)
	v_pk_add_f32 v[48:49], v[16:17], v[84:85]
	v_lshlrev_b64 v[46:47], 11, v[152:153]
	v_lshl_add_u64 v[54:55], s[54:55], 0, v[46:47]
	s_waitcnt vmcnt(0)
	v_pk_add_f32 v[16:17], v[20:21], v[150:151]
	ds_bpermute_b32 v20, v121, v160
	v_lshl_add_u64 v[152:153], v[54:55], 0, v[158:159]
	v_pk_add_f32 v[54:55], v[6:7], v[86:87]
	v_lshlrev_b64 v[6:7], 11, v[154:155]
	v_lshl_add_u64 v[6:7], s[54:55], 0, v[6:7]
	s_waitcnt lgkmcnt(0)
	v_add_f32_e32 v20, v160, v20
	ds_bpermute_b32 v21, v122, v20
	v_lshl_add_u64 v[86:87], v[6:7], 0, v[158:159]
	v_lshlrev_b64 v[6:7], 11, v[156:157]
	v_pk_add_f32 v[46:47], v[14:15], v[82:83]
	v_pk_add_f32 v[58:59], v[10:11], v[94:95]
	v_pk_add_f32 v[34:35], v[34:35], v[132:133]
	v_pk_add_f32 v[36:37], v[36:37], v[134:135]
	v_pk_add_f32 v[38:39], v[38:39], v[128:129]
	v_pk_add_f32 v[40:41], v[40:41], v[130:131]
	v_lshl_add_u64 v[10:11], s[54:55], 0, v[6:7]
	v_pk_add_f32 v[14:15], v[18:19], v[148:149]
	v_pk_add_f32 v[2:3], v[2:3], v[144:145]
	v_pk_add_f32 v[18:19], v[4:5], v[146:147]
	v_add_u32_e32 v4, s10, v123
	v_pk_add_f32 v[56:57], v[8:9], v[88:89]
	v_pk_add_f32 v[60:61], v[12:13], v[96:97]
	v_pk_add_f32 v[50:51], v[50:51], v[90:91]
	v_pk_add_f32 v[52:53], v[52:53], v[92:93]
	v_pk_add_f32 v[42:43], v[42:43], v[124:125]
	v_pk_add_f32 v[44:45], v[44:45], v[126:127]
	v_pk_add_f32 v[30:31], v[30:31], v[108:109]
	v_pk_add_f32 v[32:33], v[32:33], v[110:111]
	v_cvt_pk_bf16_f32 v82, v34, v35
	v_cvt_pk_bf16_f32 v83, v36, v37
	v_cvt_pk_bf16_f32 v84, v38, v39
	v_cvt_pk_bf16_f32 v85, v40, v41
	v_pk_add_f32 v[6:7], v[26:27], v[140:141]
	v_pk_add_f32 v[8:9], v[28:29], v[142:143]
	v_lshl_add_u64 v[88:89], v[10:11], 0, v[158:159]
	v_pk_add_f32 v[10:11], v[22:23], v[136:137]
	v_pk_add_f32 v[12:13], v[24:25], v[138:139]
	v_cvt_pk_bf16_f32 v22, v14, v15
	v_cvt_pk_bf16_f32 v23, v16, v17
	v_cvt_pk_bf16_f32 v24, v2, v3
	v_cvt_pk_bf16_f32 v25, v18, v19
	v_ashrrev_i32_e32 v5, 31, v4
	v_cvt_pk_bf16_f32 v70, v46, v47
	v_cvt_pk_bf16_f32 v71, v48, v49
	v_cvt_pk_bf16_f32 v72, v54, v55
	v_cvt_pk_bf16_f32 v73, v56, v57
	v_cvt_pk_bf16_f32 v74, v58, v59
	v_cvt_pk_bf16_f32 v75, v60, v61
	v_cvt_pk_bf16_f32 v76, v50, v51
	v_cvt_pk_bf16_f32 v77, v52, v53
	v_cvt_pk_bf16_f32 v78, v42, v43
	v_cvt_pk_bf16_f32 v79, v44, v45
	v_cvt_pk_bf16_f32 v80, v30, v31
	v_cvt_pk_bf16_f32 v81, v32, v33
	v_cvt_pk_bf16_f32 v26, v6, v7
	v_cvt_pk_bf16_f32 v27, v8, v9
	v_cvt_pk_bf16_f32 v28, v10, v11
	v_cvt_pk_bf16_f32 v29, v12, v13
	global_store_dwordx4 v[112:113], v[62:65], off
	global_store_dwordx4 v[112:113], v[66:69], off offset:64
	global_store_dwordx4 v[152:153], v[70:73], off
	global_store_dwordx4 v[152:153], v[74:77], off offset:64
	global_store_dwordx4 v[86:87], v[78:81], off
	global_store_dwordx4 v[86:87], v[82:85], off offset:64
	global_store_dwordx4 v[88:89], v[26:29], off
	global_store_dwordx4 v[88:89], v[22:25], off offset:64
	s_and_saveexec_b64 s[10:11], s[4:5]
	s_cbranch_execz .LBB0_838
	s_waitcnt lgkmcnt(0)
	v_add_f32_e32 v22, v20, v21
	v_lshl_add_u64 v[20:21], v[4:5], 2, s[0:1]
	global_atomic_add_f32 v[20:21], v22, off

.LBB0_854:
	s_add_u32 s12, s12, 0x80
	s_addc_u32 s13, s13, 0
	s_add_i32 s11, s11, 1
	s_cmp_lg_u32 s11, 6
	s_cbranch_scc1 .Ldqf_1
	s_mov_b32 s32, 0xfc37fc00
	s_mov_b32 s33, -1
	v_lshl_add_u64 v[70:71], s[32:33], 0, v[70:71]
	v_lshl_add_u64 v[66:67], s[32:33], 0, v[66:67]
	v_lshl_add_u64 v[74:75], s[32:33], 0, v[74:75]
	v_lshl_add_u64 v[78:79], s[32:33], 0, v[78:79]

.Ldqs_4:
	s_cmp_gt_u32 s11, 14
	s_cbranch_scc1 .Ldqv_4
	s_waitcnt vmcnt(4)
	s_branch .Ldqx_4

.Ldqx_4:
	s_cmpk_lg_i32 s12, 0x800
	s_mov_b32 s31, s9
	s_waitcnt lgkmcnt(0)
	s_barrier
	s_cbranch_scc0 .LBB0_869
.LBB0_855:
	s_cmp_gt_u32 s11, 14
	s_cselect_b64 s[16:17], -1, 0
	s_and_b64 vcc, exec, s[16:17]
	s_cbranch_vccnz .LBB0_857

.Ldq_4_3:
	s_waitcnt lgkmcnt(0)
	v_mfma_f32_16x16x32_bf16 v[22:25], v[128:131], v[136:139], v[22:25]
	v_add_u32_e32 v128, s100, v119
	v_add3_u32 v148, v128, v118, s101
	v_add_u32_e32 v149, v128, v117
	v_mfma_f32_16x16x32_bf16 v[42:45], v[124:127], v[132:135], v[42:45]
	s_cmp_gt_u32 s11, 13
	s_cbranch_scc1 .Ldq_4_4
	s_add_u32 s99, s100, 0x10000
	s_cmp_lt_u32 s99, 0x14000
	s_cbranch_scc1 .Ldqw_4_4
	s_sub_u32 s99, s99, 0x14000

.Ldq_4_4:
	v_mfma_f32_16x16x32_bf16 v[34:37], v[140:143], v[132:135], v[34:37]
	v_mfma_f32_16x16x32_bf16 v[38:41], v[144:147], v[132:135], v[38:41]
	s_cmp_gt_u32 s11, 13
	s_cbranch_scc1 .Ldq_4_5
	s_add_u32 m0, s99, 0x1000
	v_lshl_add_u64 v[66:67], v[66:67], 0, v[242:243]
	global_load_lds_dwordx4 v[66:67], off
.Ldq_4_5:
	v_mfma_f32_16x16x32_bf16 v[26:29], v[124:127], v[136:139], v[26:29]
	ds_read_b128 v[124:127], v148
	v_mfma_f32_16x16x32_bf16 v[18:21], v[140:143], v[136:139], v[18:21]
	s_cmp_gt_u32 s11, 13
	s_cbranch_scc1 .Ldq_4_6
	s_add_u32 m0, s99, 0x2000
	v_lshl_add_u64 v[74:75], v[74:75], 0, v[242:243]
	global_load_lds_dwordx4 v[74:75], off
.Ldq_4_6:
	v_mfma_f32_16x16x32_bf16 v[2:5], v[144:147], v[136:139], v[2:5]
	ds_read_b128 v[128:131], v148 offset:2048
	ds_read_b128 v[132:135], v149
	ds_read_b128 v[136:139], v149 offset:2048
	ds_read_b128 v[140:143], v148 offset:4096
	ds_read_b128 v[144:147], v148 offset:6144
	s_waitcnt lgkmcnt(3)
	v_mfma_f32_16x16x32_bf16 v[46:49], v[124:127], v[132:135], v[46:49]
	s_cmp_gt_u32 s11, 13
	s_cbranch_scc1 .Ldq_4_7
	s_add_u32 m0, s99, 0x3000
	v_lshl_add_u64 v[78:79], v[78:79], 0, v[242:243]
	global_load_lds_dwordx4 v[78:79], off

.LBB0_859:
	s_andn2_b64 vcc, exec, s[18:19]
	s_cbranch_vccnz .LBB0_854
	s_add_i32 s9, s31, 0x8000
	s_and_b32 s16, s9, 0x8000
	v_or_b32_e32 v124, s16, v114
	s_branch .LBB0_854
.LBB0_869:
	v_readlane_b32 s68, v237, 3
	v_readlane_b32 s69, v237, 4
	v_add_u32_e32 v112, s8, v116
	v_readlane_b32 s70, v237, 5
	v_readlane_b32 s71, v237, 6
	s_mov_b64 s[12:13], s[68:69]
	s_waitcnt vmcnt(6)
	v_add_u32_e32 v66, 0xffffc000, v112
	v_ashrrev_i32_e32 v113, 31, v112
	v_cmp_gt_i32_e32 vcc, s29, v112
	s_mov_b64 s[14:15], s[70:71]
	v_or_b32_e32 v128, s10, v120
	v_cndmask_b32_e32 v67, 0, v113, vcc
	v_cndmask_b32_e32 v66, v66, v112, vcc
	v_mov_b32_e32 v130, s15
	v_mov_b32_e32 v131, s13
	v_mov_b32_e32 v140, s14
	v_mov_b32_e32 v142, s12
	v_ashrrev_i32_e32 v129, 31, v128
	v_cndmask_b32_e32 v69, v130, v131, vcc
	v_cndmask_b32_e32 v68, v140, v142, vcc
	v_lshlrev_b64 v[66:67], 12, v[66:67]
	v_lshl_add_u64 v[66:67], v[68:69], 0, v[66:67]
	v_lshlrev_b64 v[136:137], 2, v[128:129]
	s_waitcnt vmcnt(4)
	v_lshl_add_u64 v[78:79], v[66:67], 0, v[136:137]
	global_load_dwordx4 v[66:69], v[78:79], off
	global_load_dwordx4 v[70:73], v[78:79], off offset:16
	global_load_dwordx4 v[74:77], v[78:79], off offset:128
	s_nop 0
	global_load_dwordx4 v[78:81], v[78:79], off offset:144
	v_or_b32_e32 v152, 16, v112
	s_waitcnt vmcnt(7)
	v_add_u32_e32 v82, 0xffffc010, v112
	v_ashrrev_i32_e32 v153, 31, v152
	v_cmp_gt_i32_e32 vcc, s29, v152
	v_or_b32_e32 v154, 32, v112
	v_add_u32_e32 v108, 0xffffc020, v112
	v_cndmask_b32_e32 v83, 0, v153, vcc
	v_cndmask_b32_e32 v82, v82, v152, vcc
	v_cndmask_b32_e32 v85, v130, v131, vcc
	v_cndmask_b32_e32 v84, v140, v142, vcc
	v_or_b32_e32 v156, 48, v112
	v_ashrrev_i32_e32 v155, 31, v154
	v_cmp_gt_i32_e32 vcc, s29, v154
	v_add_u32_e32 v134, 0xffffc030, v112
	v_ashrrev_i32_e32 v157, 31, v156
	v_cndmask_b32_e32 v109, 0, v155, vcc
	v_cndmask_b32_e32 v108, v108, v154, vcc
	v_cndmask_b32_e32 v111, v130, v131, vcc
	v_cndmask_b32_e32 v110, v140, v142, vcc
	v_cmp_gt_i32_e32 vcc, s29, v156
	v_lshlrev_b64 v[82:83], 12, v[82:83]
	v_lshlrev_b64 v[108:109], 12, v[108:109]
	v_cndmask_b32_e32 v139, 0, v157, vcc
	v_cndmask_b32_e32 v138, v134, v156, vcc
	v_cndmask_b32_e32 v141, v130, v131, vcc
	v_cndmask_b32_e32 v140, v140, v142, vcc
	v_lshlrev_b64 v[138:139], 12, v[138:139]
	v_lshl_add_u64 v[82:83], v[84:85], 0, v[82:83]
	v_lshl_add_u64 v[108:109], v[110:111], 0, v[108:109]
	v_lshl_add_u64 v[138:139], v[140:141], 0, v[138:139]
	s_waitcnt vmcnt(4)
	v_lshl_add_u64 v[94:95], v[82:83], 0, v[136:137]
	v_lshl_add_u64 v[132:133], v[108:109], 0, v[136:137]
	v_lshl_add_u64 v[148:149], v[138:139], 0, v[136:137]
	global_load_dwordx4 v[82:85], v[94:95], off
	global_load_dwordx4 v[86:89], v[94:95], off offset:16
	global_load_dwordx4 v[90:93], v[94:95], off offset:144
	s_nop 0
	global_load_dwordx4 v[94:97], v[94:95], off offset:128
	s_nop 0
	global_load_dwordx4 v[108:111], v[132:133], off offset:16
	global_load_dwordx4 v[124:127], v[132:133], off
	v_lshlrev_b64 v[158:159], 1, v[128:129]
	global_load_dwordx4 v[128:131], v[132:133], off offset:144
	s_nop 0
	global_load_dwordx4 v[132:135], v[132:133], off offset:128
	s_nop 0
	global_load_dwordx4 v[136:139], v[148:149], off offset:16
	global_load_dwordx4 v[140:143], v[148:149], off
	global_load_dwordx4 v[144:147], v[148:149], off offset:144
	s_nop 0
	global_load_dwordx4 v[148:151], v[148:149], off offset:128
	v_lshlrev_b64 v[112:113], 11, v[112:113]
	v_lshl_add_u64 v[112:113], s[54:55], 0, v[112:113]
	v_lshl_add_u64 v[112:113], v[112:113], 0, v[158:159]
	v_readlane_b32 s72, v237, 7
	v_readlane_b32 s73, v237, 8
	v_readlane_b32 s74, v237, 9
	v_readlane_b32 s75, v237, 10
	v_readlane_b32 s76, v237, 11
	v_readlane_b32 s77, v237, 12
	v_readlane_b32 s78, v237, 13
	v_readlane_b32 s79, v237, 14
	v_readlane_b32 s80, v237, 15
	v_readlane_b32 s81, v237, 16
	v_readlane_b32 s82, v237, 17
	v_readlane_b32 s83, v237, 18
	s_waitcnt vmcnt(15)
	v_pk_add_f32 v[46:47], v[46:47], v[66:67]
	s_waitcnt vmcnt(14)
	v_pk_add_f32 v[58:59], v[58:59], v[70:71]
	v_pk_add_f32 v[48:49], v[48:49], v[68:69]
	v_pk_add_f32 v[60:61], v[60:61], v[72:73]
	s_waitcnt vmcnt(13)
	v_pk_add_f32 v[68:69], v[62:63], v[74:75]
	v_pk_add_f32 v[70:71], v[64:65], v[76:77]
	v_cvt_pk_bf16_f32 v62, v46, v47
	v_pk_mul_f32 v[46:47], v[46:47], v[46:47]
	v_cvt_pk_bf16_f32 v64, v58, v59
	v_pk_mul_f32 v[58:59], v[58:59], v[58:59]
	v_cvt_pk_bf16_f32 v63, v48, v49
	v_pk_mul_f32 v[48:49], v[48:49], v[48:49]
	v_cvt_pk_bf16_f32 v65, v60, v61
	v_pk_mul_f32 v[60:61], v[60:61], v[60:61]
	v_pk_mul_f32 v[72:73], v[68:69], v[68:69]
	v_add_f32_e32 v58, v58, v59
	v_add_f32_e32 v46, v46, v47
	v_cvt_pk_bf16_f32 v67, v70, v71
	v_pk_mul_f32 v[70:71], v[70:71], v[70:71]
	v_add_f32_e32 v58, v58, v60
	v_add_f32_e32 v46, v46, v48
	v_add_f32_e32 v47, v72, v73
	s_waitcnt vmcnt(12)
	v_pk_add_f32 v[54:55], v[54:55], v[78:79]
	v_add_f32_e32 v58, v58, v61
	v_add_f32_e32 v46, v46, v49
	v_add_f32_e32 v47, v47, v70
	v_cvt_pk_bf16_f32 v66, v68, v69
	v_pk_add_f32 v[56:57], v[56:57], v[80:81]
	v_cvt_pk_bf16_f32 v68, v54, v55
	v_pk_mul_f32 v[54:55], v[54:55], v[54:55]
	v_add_f32_e32 v46, v46, v58
	v_add_f32_e32 v47, v47, v71
	v_cvt_pk_bf16_f32 v69, v56, v57
	v_pk_mul_f32 v[56:57], v[56:57], v[56:57]
	v_add_f32_e32 v46, v46, v47
	v_add_f32_e32 v47, v54, v55
	v_add_f32_e32 v47, v47, v56
	v_add_f32_e32 v47, v47, v57
	v_add_f32_e32 v160, v46, v47
	s_waitcnt vmcnt(11)
	v_pk_add_f32 v[48:49], v[16:17], v[84:85]
	v_lshlrev_b64 v[46:47], 11, v[152:153]
	v_lshl_add_u64 v[54:55], s[54:55], 0, v[46:47]
	s_waitcnt vmcnt(0)
	v_pk_add_f32 v[16:17], v[20:21], v[150:151]
	ds_bpermute_b32 v20, v121, v160
	v_lshl_add_u64 v[152:153], v[54:55], 0, v[158:159]
	v_pk_add_f32 v[54:55], v[6:7], v[86:87]
	v_lshlrev_b64 v[6:7], 11, v[154:155]
	v_lshl_add_u64 v[6:7], s[54:55], 0, v[6:7]
	s_waitcnt lgkmcnt(0)
	v_add_f32_e32 v20, v160, v20
	ds_bpermute_b32 v21, v122, v20
	v_lshl_add_u64 v[86:87], v[6:7], 0, v[158:159]
	v_lshlrev_b64 v[6:7], 11, v[156:157]
	v_pk_add_f32 v[46:47], v[14:15], v[82:83]
	v_pk_add_f32 v[58:59], v[10:11], v[94:95]
	v_pk_add_f32 v[34:35], v[34:35], v[132:133]
	v_pk_add_f32 v[36:37], v[36:37], v[134:135]
	v_pk_add_f32 v[38:39], v[38:39], v[128:129]
	v_pk_add_f32 v[40:41], v[40:41], v[130:131]
	v_lshl_add_u64 v[10:11], s[54:55], 0, v[6:7]
	v_pk_add_f32 v[14:15], v[18:19], v[148:149]
	v_pk_add_f32 v[2:3], v[2:3], v[144:145]
	v_pk_add_f32 v[18:19], v[4:5], v[146:147]
	v_add_u32_e32 v4, s8, v123
	v_pk_add_f32 v[56:57], v[8:9], v[88:89]
	v_pk_add_f32 v[60:61], v[12:13], v[96:97]
	v_pk_add_f32 v[50:51], v[50:51], v[90:91]
	v_pk_add_f32 v[52:53], v[52:53], v[92:93]
	v_pk_add_f32 v[42:43], v[42:43], v[124:125]
	v_pk_add_f32 v[44:45], v[44:45], v[126:127]
	v_pk_add_f32 v[30:31], v[30:31], v[108:109]
	v_pk_add_f32 v[32:33], v[32:33], v[110:111]
	v_cvt_pk_bf16_f32 v82, v34, v35
	v_cvt_pk_bf16_f32 v83, v36, v37
	v_cvt_pk_bf16_f32 v84, v38, v39
	v_cvt_pk_bf16_f32 v85, v40, v41
	v_pk_add_f32 v[6:7], v[26:27], v[140:141]
	v_pk_add_f32 v[8:9], v[28:29], v[142:143]
	v_lshl_add_u64 v[88:89], v[10:11], 0, v[158:159]
	v_pk_add_f32 v[10:11], v[22:23], v[136:137]
	v_pk_add_f32 v[12:13], v[24:25], v[138:139]
	v_cvt_pk_bf16_f32 v22, v14, v15
	v_cvt_pk_bf16_f32 v23, v16, v17
	v_cvt_pk_bf16_f32 v24, v2, v3
	v_cvt_pk_bf16_f32 v25, v18, v19
	v_ashrrev_i32_e32 v5, 31, v4
	v_cvt_pk_bf16_f32 v70, v46, v47
	v_cvt_pk_bf16_f32 v71, v48, v49
	v_cvt_pk_bf16_f32 v72, v54, v55
	v_cvt_pk_bf16_f32 v73, v56, v57
	v_cvt_pk_bf16_f32 v74, v58, v59
	v_cvt_pk_bf16_f32 v75, v60, v61
	v_cvt_pk_bf16_f32 v76, v50, v51
	v_cvt_pk_bf16_f32 v77, v52, v53
	v_cvt_pk_bf16_f32 v78, v42, v43
	v_cvt_pk_bf16_f32 v79, v44, v45
	v_cvt_pk_bf16_f32 v80, v30, v31
	v_cvt_pk_bf16_f32 v81, v32, v33
	v_cvt_pk_bf16_f32 v26, v6, v7
	v_cvt_pk_bf16_f32 v27, v8, v9
	v_cvt_pk_bf16_f32 v28, v10, v11
	v_cvt_pk_bf16_f32 v29, v12, v13
	global_store_dwordx4 v[112:113], v[62:65], off
	global_store_dwordx4 v[112:113], v[66:69], off offset:64
	global_store_dwordx4 v[152:153], v[70:73], off
	global_store_dwordx4 v[152:153], v[74:77], off offset:64
	global_store_dwordx4 v[86:87], v[78:81], off
	global_store_dwordx4 v[86:87], v[82:85], off offset:64
	global_store_dwordx4 v[88:89], v[26:29], off
	global_store_dwordx4 v[88:89], v[22:25], off offset:64
	s_and_saveexec_b64 s[8:9], s[4:5]
	s_cbranch_execz .LBB0_871
	s_waitcnt lgkmcnt(0)
	v_add_f32_e32 v22, v20, v21
	v_lshl_add_u64 v[20:21], v[4:5], 2, s[0:1]
	global_atomic_add_f32 v[20:21], v22, off

.LBB0_885:
	s_add_u32 s14, s14, 0x80
	s_addc_u32 s15, s15, 0
	s_add_i32 s11, s11, 1
	s_cmp_lg_u32 s11, 6
	s_cbranch_scc1 .Ldqf_2
	s_mov_b32 s32, 0xfc37fc00
	s_mov_b32 s33, -1
	v_lshl_add_u64 v[34:35], s[32:33], 0, v[34:35]
	v_lshl_add_u64 v[38:39], s[32:33], 0, v[38:39]

.Ldqs_6:
	s_cmp_gt_u32 s11, 14
	s_cbranch_scc1 .Ldqv_6
	s_waitcnt vmcnt(2)
	s_branch .Ldqx_6

.Ldqx_6:
	s_cmpk_lg_i32 s14, 0x800
	s_mov_b32 s5, s16
	s_waitcnt lgkmcnt(0)
	s_barrier
	s_cbranch_scc0 .LBB0_900

.Ldq_6_3:
	v_mfma_f32_16x16x32_bf16 v[22:25], v[78:81], v[82:85], v[22:25]
	s_waitcnt lgkmcnt(1)
	v_mfma_f32_16x16x32_bf16 v[26:29], v[90:93], v[82:85], v[26:29]
	s_cmp_gt_u32 s11, 13
	s_cbranch_scc1 .Ldq_6_4
	s_add_u32 s99, s100, 0x10000
	s_cmp_lt_u32 s99, 0x14000
	s_cbranch_scc1 .Ldqw_6_4
	s_sub_u32 s99, s99, 0x14000

.Ldq_6_4:
	s_waitcnt lgkmcnt(0)
	v_mfma_f32_16x16x32_bf16 v[30:33], v[94:97], v[82:85], v[30:33]
	v_mfma_f32_16x16x32_bf16 v[14:17], v[74:77], v[86:89], v[14:17]
	s_cmp_gt_u32 s11, 13
	s_cbranch_scc1 .Ldq_6_5
	s_add_u32 m0, s99, 0x1000
	v_lshl_add_u64 v[38:39], v[38:39], 0, v[242:243]
	global_load_lds_dwordx4 v[38:39], off

.LBB0_890:
	s_andn2_b64 vcc, exec, s[18:19]
	s_cbranch_vccnz .LBB0_885
	s_add_i32 s16, s5, 0x8000
	s_and_b32 s5, s16, 0x8000
	v_or_b32_e32 v73, s5, v69
	s_branch .LBB0_885
.LBB0_900:
	v_readlane_b32 s68, v237, 3
	s_waitcnt vmcnt(5)
	v_lshrrev_b32_e32 v35, 1, v0
	v_readlane_b32 s69, v237, 4
	v_and_b32_e32 v34, 64, v0
	v_add_u32_e32 v68, s4, v67
	v_and_b32_e32 v35, 24, v35
	s_movk_i32 s5, 0x4000
	v_readlane_b32 s70, v237, 5
	v_readlane_b32 s71, v237, 6
	s_mov_b64 s[12:13], s[68:69]
	v_or3_b32 v70, v35, v34, s10
	v_add_u32_e32 v34, 0xffffc000, v68
	v_ashrrev_i32_e32 v69, 31, v68
	v_cmp_gt_i32_e32 vcc, s5, v68
	s_mov_b64 s[14:15], s[70:71]
	s_waitcnt vmcnt(0)
	v_mov_b32_e32 v54, s15
	v_cndmask_b32_e32 v35, 0, v69, vcc
	v_cndmask_b32_e32 v34, v34, v68, vcc
	v_mov_b32_e32 v55, s13
	v_mov_b32_e32 v56, s14
	v_mov_b32_e32 v57, s12
	v_ashrrev_i32_e32 v71, 31, v70
	v_cndmask_b32_e32 v37, v54, v55, vcc
	v_cndmask_b32_e32 v36, v56, v57, vcc
	v_lshlrev_b64 v[34:35], 12, v[34:35]
	v_lshl_add_u64 v[34:35], v[36:37], 0, v[34:35]
	v_lshlrev_b64 v[50:51], 2, v[70:71]
	v_lshl_add_u64 v[52:53], v[34:35], 0, v[50:51]
	v_or_b32_e32 v72, 16, v68
	global_load_dwordx4 v[34:37], v[52:53], off
	global_load_dwordx4 v[38:41], v[52:53], off offset:16
	global_load_dwordx4 v[42:45], v[52:53], off offset:128
	global_load_dwordx4 v[46:49], v[52:53], off offset:144
	v_add_u32_e32 v52, 0xffffc010, v68
	v_ashrrev_i32_e32 v73, 31, v72
	v_cmp_gt_i32_e32 vcc, s5, v72
	v_lshlrev_b64 v[68:69], 11, v[68:69]
	v_lshl_add_u64 v[68:69], s[54:55], 0, v[68:69]
	v_cndmask_b32_e32 v53, 0, v73, vcc
	v_cndmask_b32_e32 v52, v52, v72, vcc
	v_cndmask_b32_e32 v55, v54, v55, vcc
	v_cndmask_b32_e32 v54, v56, v57, vcc
	v_lshlrev_b64 v[52:53], 12, v[52:53]
	v_lshl_add_u64 v[52:53], v[54:55], 0, v[52:53]
	v_lshl_add_u64 v[74:75], v[52:53], 0, v[50:51]
	global_load_dwordx4 v[50:53], v[74:75], off
	global_load_dwordx4 v[54:57], v[74:75], off offset:16
	global_load_dwordx4 v[58:61], v[74:75], off offset:128
	global_load_dwordx4 v[64:67], v[74:75], off offset:144
	v_lshlrev_b64 v[72:73], 11, v[72:73]
	v_lshlrev_b64 v[70:71], 1, v[70:71]
	v_lshl_add_u64 v[72:73], s[54:55], 0, v[72:73]
	v_lshl_add_u64 v[68:69], v[68:69], 0, v[70:71]
	v_lshl_add_u64 v[70:71], v[72:73], 0, v[70:71]
	v_readlane_b32 s72, v237, 7
	v_readlane_b32 s73, v237, 8
	v_readlane_b32 s74, v237, 9
	v_readlane_b32 s75, v237, 10
	v_readlane_b32 s76, v237, 11
	v_readlane_b32 s77, v237, 12
	v_readlane_b32 s78, v237, 13
	v_readlane_b32 s79, v237, 14
	v_readlane_b32 s80, v237, 15
	v_readlane_b32 s81, v237, 16
	v_readlane_b32 s82, v237, 17
	v_readlane_b32 s83, v237, 18
	s_waitcnt vmcnt(7)
	v_pk_add_f32 v[2:3], v[2:3], v[34:35]
	s_waitcnt vmcnt(6)
	v_pk_add_f32 v[34:35], v[22:23], v[38:39]
	v_pk_add_f32 v[4:5], v[4:5], v[36:37]
	v_pk_add_f32 v[36:37], v[24:25], v[40:41]
	s_waitcnt vmcnt(5)
	v_pk_add_f32 v[38:39], v[26:27], v[42:43]
	v_pk_add_f32 v[28:29], v[28:29], v[44:45]
	s_waitcnt vmcnt(4)
	v_pk_add_f32 v[30:31], v[30:31], v[46:47]
	v_pk_mul_f32 v[40:41], v[2:3], v[2:3]
	v_cvt_pk_bf16_f32 v24, v34, v35
	v_pk_mul_f32 v[34:35], v[34:35], v[34:35]
	v_cvt_pk_bf16_f32 v23, v4, v5
	v_pk_mul_f32 v[42:43], v[4:5], v[4:5]
	v_cvt_pk_bf16_f32 v25, v36, v37
	v_pk_mul_f32 v[36:37], v[36:37], v[36:37]
	v_cvt_pk_bf16_f32 v26, v38, v39
	v_cvt_pk_bf16_f32 v27, v28, v29
	v_pk_mul_f32 v[38:39], v[38:39], v[38:39]
	v_pk_mul_f32 v[44:45], v[28:29], v[28:29]
	v_cvt_pk_bf16_f32 v28, v30, v31
	v_pk_mul_f32 v[30:31], v[30:31], v[30:31]
	s_waitcnt vmcnt(3)
	v_pk_add_f32 v[4:5], v[16:17], v[52:53]
	s_waitcnt vmcnt(2)
	v_pk_add_f32 v[16:17], v[20:21], v[56:57]
	v_add_f32_e32 v21, v34, v35
	v_add_f32_e32 v34, v40, v41
	v_pk_add_f32 v[32:33], v[32:33], v[48:49]
	v_add_f32_e32 v35, v38, v39
	v_add_f32_e32 v30, v30, v31
	v_add_f32_e32 v21, v21, v36
	v_add_f32_e32 v31, v34, v42
	v_cvt_pk_bf16_f32 v29, v32, v33
	v_pk_mul_f32 v[32:33], v[32:33], v[32:33]
	v_add_f32_e32 v34, v35, v44
	v_add_f32_e32 v21, v21, v37
	v_add_f32_e32 v31, v31, v43
	v_cvt_pk_bf16_f32 v22, v2, v3
	v_pk_add_f32 v[2:3], v[14:15], v[50:51]
	v_add_f32_e32 v30, v30, v32
	v_add_f32_e32 v32, v34, v45
	v_add_f32_e32 v21, v31, v21
	v_pk_add_f32 v[14:15], v[18:19], v[54:55]
	v_cvt_pk_bf16_f32 v18, v2, v3
	v_add_f32_e32 v30, v30, v33
	v_add_f32_e32 v21, v21, v32
	v_cvt_pk_bf16_f32 v19, v4, v5
	v_cvt_pk_bf16_f32 v20, v14, v15
	v_add_f32_e32 v34, v21, v30
	v_cvt_pk_bf16_f32 v21, v16, v17
	global_store_dwordx4 v[68:69], v[22:25], off
	global_store_dwordx4 v[68:69], v[26:29], off offset:64
	global_store_dwordx4 v[70:71], v[18:21], off
	s_waitcnt vmcnt(4)
	v_pk_add_f32 v[10:11], v[10:11], v[58:59]
	v_pk_add_f32 v[12:13], v[12:13], v[60:61]
	v_mbcnt_lo_u32_b32 v18, -1, 0
	v_mbcnt_hi_u32_b32 v18, -1, v18
	v_and_b32_e32 v20, 64, v18
	v_xor_b32_e32 v19, 16, v18
	v_add_u32_e32 v21, 64, v20
	v_cmp_lt_i32_e32 vcc, v19, v21
	v_xor_b32_e32 v22, 32, v18
	s_waitcnt vmcnt(3)
	v_pk_add_f32 v[6:7], v[6:7], v[64:65]
	v_cndmask_b32_e32 v19, v18, v19, vcc
	v_lshlrev_b32_e32 v20, 2, v19
	ds_bpermute_b32 v19, v20, v34
	v_cmp_lt_i32_e32 vcc, v22, v21
	v_pk_add_f32 v[8:9], v[8:9], v[66:67]
	v_cvt_pk_bf16_f32 v30, v10, v11
	v_cndmask_b32_e32 v18, v18, v22, vcc
	v_lshlrev_b32_e32 v21, 2, v18
	s_waitcnt lgkmcnt(0)
	v_add_f32_e32 v22, v34, v19
	ds_bpermute_b32 v23, v21, v22
	v_add3_u32 v18, v63, v1, s4
	v_cvt_pk_bf16_f32 v31, v12, v13
	v_cvt_pk_bf16_f32 v32, v6, v7
	v_cvt_pk_bf16_f32 v33, v8, v9
	v_cmp_gt_u32_e32 vcc, 16, v1
	v_ashrrev_i32_e32 v19, 31, v18
	global_store_dwordx4 v[70:71], v[30:33], off offset:64
	s_and_saveexec_b64 s[4:5], vcc
	s_cbranch_execz .LBB0_902
	s_waitcnt lgkmcnt(0)
	v_add_f32_e32 v24, v22, v23
	v_lshl_add_u64 v[22:23], v[18:19], 2, s[0:1]
	global_atomic_add_f32 v[22:23], v24, off

.LBB0_914:
	s_add_u32 s10, s10, 0x80
	s_addc_u32 s11, s11, 0
	s_add_i32 s9, s9, 1
	s_cmp_lg_u32 s9, 6
	s_cbranch_scc1 .Ldqf_3
	s_mov_b32 s32, 0xfc37fc00
	s_mov_b32 s33, -1
	v_lshl_add_u64 v[70:71], s[32:33], 0, v[70:71]
	v_lshl_add_u64 v[66:67], s[32:33], 0, v[66:67]
	v_lshl_add_u64 v[74:75], s[32:33], 0, v[74:75]
	v_lshl_add_u64 v[78:79], s[32:33], 0, v[78:79]

.Ldqx_8:
	s_cmpk_lg_i32 s10, 0x800
	s_mov_b32 s27, s7
	s_waitcnt lgkmcnt(0)
	s_barrier
	s_cbranch_scc0 .LBB0_929
.LBB0_915:
	s_cmp_gt_u32 s9, 14
	s_cselect_b64 s[14:15], -1, 0
	s_and_b64 vcc, exec, s[14:15]
	s_cbranch_vccnz .LBB0_917
.LBB0_917:
	v_add_u32_e32 v128, s100, v115
	v_add3_u32 v144, v128, v118, s101
	ds_read_b128 v[124:127], v144
	v_add_u32_e32 v148, v128, v117
	ds_read_b128 v[128:131], v144 offset:2048
	ds_read_b128 v[132:135], v148
	ds_read_b128 v[136:139], v148 offset:2048
	ds_read_b128 v[140:143], v144 offset:4096
	ds_read_b128 v[144:147], v144 offset:6144
	s_waitcnt lgkmcnt(3)
	v_mfma_f32_16x16x32_bf16 v[58:61], v[128:131], v[132:135], v[58:61]
	s_mov_b64 s[16:17], -1
	s_andn2_b64 vcc, exec, s[14:15]
	v_mfma_f32_16x16x32_bf16 v[46:49], v[124:127], v[132:135], v[46:49]
	s_waitcnt lgkmcnt(1)
	v_mfma_f32_16x16x32_bf16 v[62:65], v[140:143], v[132:135], v[62:65]
	s_cbranch_vccz .Ldq_8_0
	s_add_u32 s99, s100, 0xc000
	s_cmp_lt_u32 s99, 0x14000
	s_cbranch_scc1 .Ldqw_8_0
	s_sub_u32 s99, s99, 0x14000

.Ldq_8_3:
	s_waitcnt lgkmcnt(0)
	v_mfma_f32_16x16x32_bf16 v[22:25], v[128:131], v[136:139], v[22:25]
	v_add_u32_e32 v128, s100, v119
	v_add3_u32 v148, v128, v118, s101
	v_add_u32_e32 v149, v128, v117
	v_mfma_f32_16x16x32_bf16 v[42:45], v[124:127], v[132:135], v[42:45]
	s_cmp_gt_u32 s9, 13
	s_cbranch_scc1 .Ldq_8_4
	s_add_u32 s99, s100, 0x10000
	s_cmp_lt_u32 s99, 0x14000
	s_cbranch_scc1 .Ldqw_8_4
	s_sub_u32 s99, s99, 0x14000

.Ldq_8_4:
	v_mfma_f32_16x16x32_bf16 v[34:37], v[140:143], v[132:135], v[34:37]
	v_mfma_f32_16x16x32_bf16 v[38:41], v[144:147], v[132:135], v[38:41]
	s_cmp_gt_u32 s9, 13
	s_cbranch_scc1 .Ldq_8_5
	s_add_u32 m0, s99, 0x1000
	v_lshl_add_u64 v[66:67], v[66:67], 0, v[242:243]
	global_load_lds_dwordx4 v[66:67], off
.Ldq_8_5:
	v_mfma_f32_16x16x32_bf16 v[26:29], v[124:127], v[136:139], v[26:29]
	ds_read_b128 v[124:127], v148
	v_mfma_f32_16x16x32_bf16 v[18:21], v[140:143], v[136:139], v[18:21]
	s_cmp_gt_u32 s9, 13
	s_cbranch_scc1 .Ldq_8_6
	s_add_u32 m0, s99, 0x2000
	v_lshl_add_u64 v[74:75], v[74:75], 0, v[242:243]
	global_load_lds_dwordx4 v[74:75], off
.Ldq_8_6:
	v_mfma_f32_16x16x32_bf16 v[2:5], v[144:147], v[136:139], v[2:5]
	ds_read_b128 v[128:131], v148 offset:2048
	ds_read_b128 v[132:135], v149
	ds_read_b128 v[136:139], v149 offset:2048
	ds_read_b128 v[140:143], v148 offset:4096
	ds_read_b128 v[144:147], v148 offset:6144
	s_waitcnt lgkmcnt(3)
	v_mfma_f32_16x16x32_bf16 v[46:49], v[124:127], v[132:135], v[46:49]
	s_cmp_gt_u32 s9, 13
	s_cbranch_scc1 .Ldq_8_7
	s_add_u32 m0, s99, 0x3000
	v_lshl_add_u64 v[78:79], v[78:79], 0, v[242:243]
	global_load_lds_dwordx4 v[78:79], off

.LBB0_919:
	s_andn2_b64 vcc, exec, s[16:17]
	s_cbranch_vccnz .LBB0_914
	s_add_i32 s7, s27, 0x8000
	s_and_b32 s14, s7, 0x8000
	v_or_b32_e32 v124, s14, v114
	s_branch .LBB0_914
.LBB0_929:
	v_readlane_b32 s68, v237, 3
	v_readlane_b32 s69, v237, 4
	v_add_u32_e32 v112, s6, v116
	v_or_b32_e32 v128, s8, v120
	v_readlane_b32 s70, v237, 5
	v_readlane_b32 s71, v237, 6
	s_mov_b64 s[8:9], s[68:69]
	s_waitcnt vmcnt(6)
	v_add_u32_e32 v66, 0xffffc000, v112
	v_ashrrev_i32_e32 v113, 31, v112
	v_cmp_gt_i32_e32 vcc, s26, v112
	s_mov_b64 s[10:11], s[70:71]
	v_mov_b32_e32 v130, s11
	v_cndmask_b32_e32 v67, 0, v113, vcc
	v_cndmask_b32_e32 v66, v66, v112, vcc
	v_mov_b32_e32 v131, s9
	v_mov_b32_e32 v140, s10
	v_mov_b32_e32 v142, s8
	v_ashrrev_i32_e32 v129, 31, v128
	v_cndmask_b32_e32 v69, v130, v131, vcc
	v_cndmask_b32_e32 v68, v140, v142, vcc
	v_lshlrev_b64 v[66:67], 12, v[66:67]
	v_lshl_add_u64 v[66:67], v[68:69], 0, v[66:67]
	v_lshlrev_b64 v[136:137], 2, v[128:129]
	s_waitcnt vmcnt(3)
	v_lshl_add_u64 v[82:83], v[66:67], 0, v[136:137]
	global_load_dwordx4 v[66:69], v[82:83], off
	global_load_dwordx4 v[70:73], v[82:83], off offset:16
	global_load_dwordx4 v[74:77], v[82:83], off offset:128
	global_load_dwordx4 v[78:81], v[82:83], off offset:144
	v_or_b32_e32 v152, 16, v112
	v_add_u32_e32 v82, 0xffffc010, v112
	v_ashrrev_i32_e32 v153, 31, v152
	v_cmp_gt_i32_e32 vcc, s26, v152
	v_or_b32_e32 v154, 32, v112
	v_add_u32_e32 v108, 0xffffc020, v112
	v_cndmask_b32_e32 v83, 0, v153, vcc
	v_cndmask_b32_e32 v82, v82, v152, vcc
	v_cndmask_b32_e32 v85, v130, v131, vcc
	v_cndmask_b32_e32 v84, v140, v142, vcc
	v_or_b32_e32 v156, 48, v112
	v_ashrrev_i32_e32 v155, 31, v154
	v_cmp_gt_i32_e32 vcc, s26, v154
	v_add_u32_e32 v134, 0xffffc030, v112
	v_ashrrev_i32_e32 v157, 31, v156
	v_cndmask_b32_e32 v109, 0, v155, vcc
	v_cndmask_b32_e32 v108, v108, v154, vcc
	v_cndmask_b32_e32 v111, v130, v131, vcc
	v_cndmask_b32_e32 v110, v140, v142, vcc
	v_cmp_gt_i32_e32 vcc, s26, v156
	v_lshlrev_b64 v[82:83], 12, v[82:83]
	v_lshlrev_b64 v[108:109], 12, v[108:109]
	v_cndmask_b32_e32 v139, 0, v157, vcc
	v_cndmask_b32_e32 v138, v134, v156, vcc
	v_cndmask_b32_e32 v141, v130, v131, vcc
	v_cndmask_b32_e32 v140, v140, v142, vcc
	v_lshlrev_b64 v[138:139], 12, v[138:139]
	v_lshl_add_u64 v[82:83], v[84:85], 0, v[82:83]
	v_lshl_add_u64 v[108:109], v[110:111], 0, v[108:109]
	v_lshl_add_u64 v[138:139], v[140:141], 0, v[138:139]
	s_waitcnt vmcnt(4)
	v_lshl_add_u64 v[94:95], v[82:83], 0, v[136:137]
	v_lshl_add_u64 v[132:133], v[108:109], 0, v[136:137]
	v_lshl_add_u64 v[148:149], v[138:139], 0, v[136:137]
	global_load_dwordx4 v[82:85], v[94:95], off
	global_load_dwordx4 v[86:89], v[94:95], off offset:16
	global_load_dwordx4 v[90:93], v[94:95], off offset:144
	s_nop 0
	global_load_dwordx4 v[94:97], v[94:95], off offset:128
	s_nop 0
	global_load_dwordx4 v[108:111], v[132:133], off offset:16
	global_load_dwordx4 v[124:127], v[132:133], off
	v_lshlrev_b64 v[158:159], 1, v[128:129]
	global_load_dwordx4 v[128:131], v[132:133], off offset:144
	s_nop 0
	global_load_dwordx4 v[132:135], v[132:133], off offset:128
	s_nop 0
	global_load_dwordx4 v[136:139], v[148:149], off offset:16
	global_load_dwordx4 v[140:143], v[148:149], off
	global_load_dwordx4 v[144:147], v[148:149], off offset:144
	s_nop 0
	global_load_dwordx4 v[148:151], v[148:149], off offset:128
	v_lshlrev_b64 v[112:113], 11, v[112:113]
	v_lshl_add_u64 v[112:113], s[54:55], 0, v[112:113]
	v_lshl_add_u64 v[112:113], v[112:113], 0, v[158:159]
	v_readlane_b32 s72, v237, 7
	v_readlane_b32 s73, v237, 8
	v_readlane_b32 s74, v237, 9
	v_readlane_b32 s75, v237, 10
	v_readlane_b32 s76, v237, 11
	v_readlane_b32 s77, v237, 12
	v_readlane_b32 s78, v237, 13
	v_readlane_b32 s79, v237, 14
	v_readlane_b32 s80, v237, 15
	v_readlane_b32 s81, v237, 16
	v_readlane_b32 s82, v237, 17
	v_readlane_b32 s83, v237, 18
	s_waitcnt vmcnt(15)
	v_pk_add_f32 v[46:47], v[46:47], v[66:67]
	s_waitcnt vmcnt(14)
	v_pk_add_f32 v[58:59], v[58:59], v[70:71]
	v_pk_add_f32 v[48:49], v[48:49], v[68:69]
	v_pk_add_f32 v[60:61], v[60:61], v[72:73]
	s_waitcnt vmcnt(13)
	v_pk_add_f32 v[68:69], v[62:63], v[74:75]
	v_pk_add_f32 v[70:71], v[64:65], v[76:77]
	v_cvt_pk_bf16_f32 v62, v46, v47
	v_pk_mul_f32 v[46:47], v[46:47], v[46:47]
	v_cvt_pk_bf16_f32 v64, v58, v59
	v_pk_mul_f32 v[58:59], v[58:59], v[58:59]
	v_cvt_pk_bf16_f32 v63, v48, v49
	v_pk_mul_f32 v[48:49], v[48:49], v[48:49]
	v_cvt_pk_bf16_f32 v65, v60, v61
	v_pk_mul_f32 v[60:61], v[60:61], v[60:61]
	v_pk_mul_f32 v[72:73], v[68:69], v[68:69]
	v_add_f32_e32 v58, v58, v59
	v_add_f32_e32 v46, v46, v47
	v_cvt_pk_bf16_f32 v67, v70, v71
	v_pk_mul_f32 v[70:71], v[70:71], v[70:71]
	v_add_f32_e32 v58, v58, v60
	v_add_f32_e32 v46, v46, v48
	v_add_f32_e32 v47, v72, v73
	s_waitcnt vmcnt(12)
	v_pk_add_f32 v[54:55], v[54:55], v[78:79]
	v_add_f32_e32 v58, v58, v61
	v_add_f32_e32 v46, v46, v49
	v_add_f32_e32 v47, v47, v70
	v_cvt_pk_bf16_f32 v66, v68, v69
	v_pk_add_f32 v[56:57], v[56:57], v[80:81]
	v_cvt_pk_bf16_f32 v68, v54, v55
	v_pk_mul_f32 v[54:55], v[54:55], v[54:55]
	v_add_f32_e32 v46, v46, v58
	v_add_f32_e32 v47, v47, v71
	v_cvt_pk_bf16_f32 v69, v56, v57
	v_pk_mul_f32 v[56:57], v[56:57], v[56:57]
	v_add_f32_e32 v46, v46, v47
	v_add_f32_e32 v47, v54, v55
	v_add_f32_e32 v47, v47, v56
	v_add_f32_e32 v47, v47, v57
	v_add_f32_e32 v160, v46, v47
	s_waitcnt vmcnt(11)
	v_pk_add_f32 v[48:49], v[16:17], v[84:85]
	v_lshlrev_b64 v[46:47], 11, v[152:153]
	v_lshl_add_u64 v[54:55], s[54:55], 0, v[46:47]
	s_waitcnt vmcnt(0)
	v_pk_add_f32 v[16:17], v[20:21], v[150:151]
	ds_bpermute_b32 v20, v121, v160
	v_lshl_add_u64 v[152:153], v[54:55], 0, v[158:159]
	v_pk_add_f32 v[54:55], v[6:7], v[86:87]
	v_lshlrev_b64 v[6:7], 11, v[154:155]
	v_lshl_add_u64 v[6:7], s[54:55], 0, v[6:7]
	s_waitcnt lgkmcnt(0)
	v_add_f32_e32 v20, v160, v20
	ds_bpermute_b32 v21, v122, v20
	v_lshl_add_u64 v[86:87], v[6:7], 0, v[158:159]
	v_lshlrev_b64 v[6:7], 11, v[156:157]
	v_pk_add_f32 v[46:47], v[14:15], v[82:83]
	v_pk_add_f32 v[58:59], v[10:11], v[94:95]
	v_pk_add_f32 v[34:35], v[34:35], v[132:133]
	v_pk_add_f32 v[36:37], v[36:37], v[134:135]
	v_pk_add_f32 v[38:39], v[38:39], v[128:129]
	v_pk_add_f32 v[40:41], v[40:41], v[130:131]
	v_lshl_add_u64 v[10:11], s[54:55], 0, v[6:7]
	v_pk_add_f32 v[14:15], v[18:19], v[148:149]
	v_pk_add_f32 v[2:3], v[2:3], v[144:145]
	v_pk_add_f32 v[18:19], v[4:5], v[146:147]
	v_add_u32_e32 v4, s6, v123
	v_pk_add_f32 v[56:57], v[8:9], v[88:89]
	v_pk_add_f32 v[60:61], v[12:13], v[96:97]
	v_pk_add_f32 v[50:51], v[50:51], v[90:91]
	v_pk_add_f32 v[52:53], v[52:53], v[92:93]
	v_pk_add_f32 v[42:43], v[42:43], v[124:125]
	v_pk_add_f32 v[44:45], v[44:45], v[126:127]
	v_pk_add_f32 v[30:31], v[30:31], v[108:109]
	v_pk_add_f32 v[32:33], v[32:33], v[110:111]
	v_cvt_pk_bf16_f32 v82, v34, v35
	v_cvt_pk_bf16_f32 v83, v36, v37
	v_cvt_pk_bf16_f32 v84, v38, v39
	v_cvt_pk_bf16_f32 v85, v40, v41
	v_pk_add_f32 v[6:7], v[26:27], v[140:141]
	v_pk_add_f32 v[8:9], v[28:29], v[142:143]
	v_lshl_add_u64 v[88:89], v[10:11], 0, v[158:159]
	v_pk_add_f32 v[10:11], v[22:23], v[136:137]
	v_pk_add_f32 v[12:13], v[24:25], v[138:139]
	v_cvt_pk_bf16_f32 v22, v14, v15
	v_cvt_pk_bf16_f32 v23, v16, v17
	v_cvt_pk_bf16_f32 v24, v2, v3
	v_cvt_pk_bf16_f32 v25, v18, v19
	v_ashrrev_i32_e32 v5, 31, v4
	v_cvt_pk_bf16_f32 v70, v46, v47
	v_cvt_pk_bf16_f32 v71, v48, v49
	v_cvt_pk_bf16_f32 v72, v54, v55
	v_cvt_pk_bf16_f32 v73, v56, v57
	v_cvt_pk_bf16_f32 v74, v58, v59
	v_cvt_pk_bf16_f32 v75, v60, v61
	v_cvt_pk_bf16_f32 v76, v50, v51
	v_cvt_pk_bf16_f32 v77, v52, v53
	v_cvt_pk_bf16_f32 v78, v42, v43
	v_cvt_pk_bf16_f32 v79, v44, v45
	v_cvt_pk_bf16_f32 v80, v30, v31
	v_cvt_pk_bf16_f32 v81, v32, v33
	v_cvt_pk_bf16_f32 v26, v6, v7
	v_cvt_pk_bf16_f32 v27, v8, v9
	v_cvt_pk_bf16_f32 v28, v10, v11
	v_cvt_pk_bf16_f32 v29, v12, v13
	global_store_dwordx4 v[112:113], v[62:65], off
	global_store_dwordx4 v[112:113], v[66:69], off offset:64
	global_store_dwordx4 v[152:153], v[70:73], off
	global_store_dwordx4 v[152:153], v[74:77], off offset:64
	global_store_dwordx4 v[86:87], v[78:81], off
	global_store_dwordx4 v[86:87], v[82:85], off offset:64
	global_store_dwordx4 v[88:89], v[26:29], off
	global_store_dwordx4 v[88:89], v[22:25], off offset:64
	s_and_saveexec_b64 s[6:7], s[4:5]
	s_cbranch_execz .LBB0_931
	s_waitcnt lgkmcnt(0)
	v_add_f32_e32 v22, v20, v21
	v_lshl_add_u64 v[20:21], v[4:5], 2, s[0:1]
	global_atomic_add_f32 v[20:21], v22, off
